# kernel-wide static s_setprio 1 for waves 4-7 only (GEMM flips deleted, no attention raise)
# baseline (speedup 1.0000x reference)
; #define LAS __attribute__((address_space(3)))
; __device__ __forceinline__ unsigned xb_add(unsigned* p, unsigned v) { return __hip_atomic_fetch_add(p, v, __ATOMIC_RELAXED, __HIP_MEMORY_SCOPE_AGENT); }
; __device__ __forceinline__ unsigned xb_xcc_id() { return (unsigned)__builtin_amdgcn_s_getreg((3 << 11) | 20) & 0xFu; }
; __device__ __forceinline__ CArgs argp() { CArgs p = (CArgs)__builtin_amdgcn_kernarg_segment_ptr(); asm volatile("" : "+s"(p)); return p; }
; __global__ void __launch_bounds__(NWAVES * 64, 2) mega_fwd(Args a_unused) {
;     extern __shared__ __attribute__((aligned(16))) unsigned char lds_raw[];
;     LAS unsigned char* lds = (LAS unsigned char*)lds_raw;
;     cg::grid_group grid = cg::this_grid();
;     volatile LAS unsigned* bst = (volatile LAS unsigned*)(lds + 131072);
;     if (threadIdx.x < 8) bst[threadIdx.x] = 0u;
;     __syncthreads();
;     if (threadIdx.x == 0) { unsigned* bar_ = (unsigned*)(argp()->ws + WS_BAR); const unsigned x_ = xb_xcc_id(); bst[2] = x_; bst[3] = xb_add(&bar_[XB_XCNT(x_)], 1u); }
_Z8mega_fwd4Args:
	s_load_dwordx2 s[82:83], s[0:1], 0x90
	s_load_dword s72, s[0:1], 0x98
	s_add_u32 s16, s0, 0x90
	v_and_b32_e32 v171, 0x3ff, v0
	s_addc_u32 s17, s1, 0
	v_readfirstlane_b32 s98, v171
	s_nop 3
	s_cmpk_ge_u32 s98, 0x100
	s_cbranch_scc0 .Lk_noprio
	s_setprio 1
